# retention-output chunk loops: 50 f32->bf16 pair packs via v_cvt_pk_bf16_f32 (peephole with liveness checks)
# baseline (speedup 1.0000x reference)
; #define UFOR(v, n) _Pragma("unroll") for (int v = 0; v < (n); ++v)
; __device__ __forceinline__ unsigned pk2(float a, float b) { return (unsigned)f2bf(a) | ((unsigned)f2bf(b) << 16); }
; __device__ __forceinline__ void ret_stage(const RetRaw& R, int tid_, int mode, int rope, float zf, float zb) {
;     ...
;   unpack8(R.k1, k1); unpack8(R.k2, k2); unpack8(R.v1, v1); unpack8(R.v2, v2);
;   if (mode == 0) { unpack8(R.q1, q1); unpack8(R.q2, q2); }
;   if (rope) {
;     const float cc[8] = {R.c0.x, R.c0.y, R.c0.z, R.c0.w, R.c1.x, R.c1.y, R.c1.z, R.c1.w};
;     const float ss[8] = {R.s0.x, R.s0.y, R.s0.z, R.s0.w, R.s1.x, R.s1.y, R.s1.z, R.s1.w};
;     UFOR(x, 8) {
;       const float c = cc[x], s = ss[x];
;       const float a = k1[x], b = k2[x]; k1[x] = a * c - b * s; k2[x] = a * s + b * c;
;       if (mode == 0) { const float a2 = q1[x], b2 = q2[x]; q1[x] = a2 * c - b2 * s; q2[x] = a2 * s + b2 * c; }
;     }
;   }
; __device__ __forceinline__ void ret_pass(KP p, int tid_, int dir, int n0, int nch, int h, int rope, int tseg0, f32x4* RT, float* scr) {
;     ...
;     UFOR(n, 8) {
;       uint2 pk; pk.x = pk2(RT[n][0], RT[n][1]); pk.y = pk2(RT[n][2], RT[n][3]);
;       *(uint2*)(smem + R_RT + (w * 16 + fr) * 272 + (n * 16 + fq * 4) * 2) = pk;
;     }
;     ret_stage(R, tid_, 0, rope, pw[63 - (tid_ >> 3)], 0.f);
.LBB0_404:
	s_waitcnt vmcnt(11)
	v_cvt_pk_bf16_f32 v73, v2, v3
	v_cvt_pk_bf16_f32 v72, v0, v1
	v_add_u32_e32 v76, v157, v158
	v_cvt_pk_bf16_f32 v75, v6, v7
	v_cvt_pk_bf16_f32 v74, v4, v5
	s_waitcnt lgkmcnt(0)
	s_barrier
	ds_write2_b64 v76, v[72:73], v[74:75] offset1:4
	v_cvt_pk_bf16_f32 v73, v10, v11
	v_cvt_pk_bf16_f32 v72, v8, v9
	s_waitcnt vmcnt(10)
	v_cvt_pk_bf16_f32 v75, v14, v15
	v_cvt_pk_bf16_f32 v74, v12, v13
	ds_write2_b64 v76, v[72:73], v[74:75] offset0:8 offset1:12
	s_waitcnt vmcnt(9)
	v_cvt_pk_bf16_f32 v73, v18, v19
	v_cvt_pk_bf16_f32 v72, v16, v17
	s_waitcnt vmcnt(8)
	v_cvt_pk_bf16_f32 v75, v22, v23
	v_cvt_pk_bf16_f32 v74, v20, v21
	ds_write2_b64 v76, v[72:73], v[74:75] offset0:16 offset1:20
	s_waitcnt vmcnt(7)
	v_cvt_pk_bf16_f32 v73, v26, v27
	v_cvt_pk_bf16_f32 v72, v24, v25
	s_waitcnt vmcnt(6)
	v_cvt_pk_bf16_f32 v75, v30, v31
	v_cvt_pk_bf16_f32 v74, v28, v29
	ds_write2_b64 v76, v[72:73], v[74:75] offset0:24 offset1:28
	ds_read_b32 v220, v159
	s_waitcnt vmcnt(1)
	v_lshlrev_b32_e32 v82, 16, v51
	v_lshlrev_b32_e32 v78, 16, v48
	v_and_b32_e32 v79, 0xffff0000, v48
	v_lshlrev_b32_e32 v72, 16, v32
	v_and_b32_e32 v73, 0xffff0000, v32
	v_lshlrev_b32_e32 v84, 16, v49
	v_and_b32_e32 v85, 0xffff0000, v49
	v_lshlrev_b32_e32 v76, 16, v33
	v_and_b32_e32 v77, 0xffff0000, v33
	v_lshlrev_b32_e32 v80, 16, v50
	v_and_b32_e32 v81, 0xffff0000, v50
	v_lshlrev_b32_e32 v74, 16, v34
	v_and_b32_e32 v75, 0xffff0000, v34
	v_lshlrev_b32_e32 v86, 16, v35
	v_and_b32_e32 v121, 0xffff0000, v51
	v_and_b32_e32 v120, 0xffff0000, v35
	v_lshlrev_b32_e32 v131, 16, v47
	v_lshlrev_b32_e32 v140, 16, v44
	v_and_b32_e32 v141, 0xffff0000, v44
	s_waitcnt vmcnt(0)
	v_lshlrev_b32_e32 v128, 16, v52
	v_and_b32_e32 v129, 0xffff0000, v52
	v_lshlrev_b32_e32 v126, 16, v45
	v_and_b32_e32 v127, 0xffff0000, v45
	v_lshlrev_b32_e32 v122, 16, v53
	v_and_b32_e32 v123, 0xffff0000, v53
	v_lshlrev_b32_e32 v130, 16, v46
	v_and_b32_e32 v151, 0xffff0000, v46
	v_lshlrev_b32_e32 v124, 16, v54
	v_and_b32_e32 v147, 0xffff0000, v54
	v_lshlrev_b32_e32 v125, 16, v55
	v_and_b32_e32 v143, 0xffff0000, v47
	s_and_b64 vcc, exec, s[74:75]
	v_and_b32_e32 v142, 0xffff0000, v55
	s_cbranch_vccnz .LBB0_406
	v_mov_b32_e32 v240, v67
	v_mov_b32_e32 v241, v63
	v_mov_b32_e32 v146, v124
	v_mul_f32_e32 v124, v62, v82
	v_mul_f32_e32 v230, v66, v82
	v_pk_mul_f32 v[82:83], v[240:241], v[120:121]
	v_mov_b32_e32 v150, v130
	v_mul_f32_e32 v130, v66, v86
	v_mul_f32_e32 v232, v62, v131
	v_mul_f32_e32 v234, v66, v125
	v_mul_f32_e32 v236, v66, v131
	v_mul_f32_e32 v238, v62, v125
	v_mov_b32_e32 v125, v83
	v_mov_b32_e32 v131, v82
	v_pk_add_f32 v[82:83], v[124:125], v[130:131] neg_lo:[0,1] neg_hi:[0,1]
	v_mov_b32_e32 v124, v63
	v_mov_b32_e32 v125, v67
	v_pk_mul_f32 v[120:121], v[124:125], v[120:121]
	v_pk_mul_f32 v[136:137], v[68:69], v[72:73]
	v_mov_b32_e32 v87, v120
	v_mov_b32_e32 v231, v121
	v_pk_mul_f32 v[120:121], v[240:241], v[142:143]
	v_pk_mul_f32 v[138:139], v[68:69], v[78:79]
	v_mov_b32_e32 v233, v121
	v_mov_b32_e32 v235, v120
	v_pk_mul_f32 v[120:121], v[124:125], v[142:143]
	v_pk_mul_f32 v[144:145], v[68:69], v[128:129]
	v_pk_mul_f32 v[208:209], v[68:69], v[140:141]
	v_pk_mul_f32 v[148:149], v[70:71], v[76:77]
	v_pk_mul_f32 v[214:215], v[70:71], v[122:123]
	v_pk_mul_f32 v[216:217], v[70:71], v[126:127]
	v_pk_mul_f32 v[226:227], v[64:65], v[146:147]
	v_pk_mul_f32 v[228:229], v[64:65], v[150:151]
	v_mul_f32_e32 v86, v62, v86
	v_mov_b32_e32 v239, v120
	v_mov_b32_e32 v237, v121
	v_pk_mul_f32 v[210:211], v[70:71], v[84:85]
	v_pk_mul_f32 v[222:223], v[64:65], v[74:75]
	v_pk_mul_f32 v[224:225], v[64:65], v[80:81]
	v_pk_fma_f32 v[78:79], v[56:57], v[78:79], v[136:137] neg_lo:[0,0,1] neg_hi:[0,0,1]
	v_pk_fma_f32 v[84:85], v[58:59], v[84:85], v[148:149] neg_lo:[0,0,1] neg_hi:[0,0,1]
	v_pk_fma_f32 v[72:73], v[56:57], v[72:73], v[138:139]
	v_pk_add_f32 v[86:87], v[86:87], v[230:231]
	v_pk_fma_f32 v[148:149], v[56:57], v[140:141], v[144:145] neg_lo:[0,0,1] neg_hi:[0,0,1]
	v_pk_fma_f32 v[126:127], v[58:59], v[126:127], v[214:215] neg_lo:[0,0,1] neg_hi:[0,0,1]
	v_pk_fma_f32 v[130:131], v[60:61], v[150:151], v[226:227] neg_lo:[0,0,1] neg_hi:[0,0,1]
	v_pk_add_f32 v[136:137], v[232:233], v[234:235] neg_lo:[0,1] neg_hi:[0,1]
	v_pk_fma_f32 v[144:145], v[56:57], v[128:129], v[208:209]
	v_pk_fma_f32 v[122:123], v[58:59], v[122:123], v[216:217]
	v_pk_fma_f32 v[124:125], v[60:61], v[146:147], v[228:229]
	v_pk_add_f32 v[138:139], v[238:239], v[236:237]
	v_pk_fma_f32 v[80:81], v[60:61], v[80:81], v[222:223] neg_lo:[0,0,1] neg_hi:[0,0,1]
	v_pk_fma_f32 v[76:77], v[58:59], v[76:77], v[210:211]
	v_pk_fma_f32 v[74:75], v[60:61], v[74:75], v[224:225]
	v_mov_b32_e32 v120, v87
	v_mov_b32_e32 v121, v83
	v_mov_b32_e32 v129, v145
	v_mov_b32_e32 v145, v122
	v_mov_b32_e32 v146, v125
	v_mov_b32_e32 v125, v138
	v_mov_b32_e32 v147, v139
	v_mov_b32_e32 v141, v149
	v_mov_b32_e32 v149, v126
	v_mov_b32_e32 v142, v131
	v_mov_b32_e32 v131, v136
	v_mov_b32_e32 v143, v137
	s_branch .LBB0_407

; #define UFOR(v, n) _Pragma("unroll") for (int v = 0; v < (n); ++v)
; __device__ __forceinline__ void ret_stage(const RetRaw& R, int tid_, int mode, int rope, float zf, float zb) {
;     ...
;   u16* VT = (u16*)(smem + R_VT);
;   const int isw = i ^ (g << 3);
;   UFOR(x, 8) { VT[(g * 8 + x) * 72 + isw] = f2bf(v1[x]); VT[(64 + g * 8 + x) * 72 + isw] = f2bf(v2[x]); }
;   u16* KT = (u16*)(smem + R_KT);
;   UFOR(x, 8) { KT[(g * 8 + x) * 72 + isw] = f2bf(k1[x] * zf); KT[(64 + g * 8 + x) * 72 + isw] = f2bf(k2[x] * zf); }
;   if (mode == 1) {
;     u16* KB = (u16*)(smem + R_KT2B);
;     UFOR(x, 8) { KB[(g * 8 + x) * 72 + isw] = f2bf(k1[x] * zb); KB[(64 + g * 8 + x) * 72 + isw] = f2bf(k2[x] * zb); }
;   } else {
;     const float sc = 0.08838834764831845f;
;     UFOR(x, 8) { q1[x] *= sc; q2[x] *= sc; }
;     *(uint4*)(smem + R_QS + i * 272 + g * 16) = pack8(q1); *(uint4*)(smem + R_QS + i * 272 + 128 + g * 16) = pack8(q2);
;     *(uint4*)(smem + R_KS + i * 272 + g * 16) = pack8(k1); *(uint4*)(smem + R_KS + i * 272 + 128 + g * 16) = pack8(k2);
;   }
.LBB0_407:
	s_waitcnt lgkmcnt(0)
	v_mul_f32_e32 v83, v220, v78
	v_bfe_u32 v87, v83, 16, 1
	v_add3_u32 v83, v83, v87, s31
	ds_write_b16 v161, v36 offset:53248
	ds_write_b16 v162, v40 offset:62464
	ds_write_b16_d16_hi v161, v36 offset:53392
	ds_write_b16_d16_hi v162, v40 offset:62608
	ds_write_b16 v161, v37 offset:53536
	ds_write_b16 v162, v41 offset:62752
	ds_write_b16_d16_hi v161, v37 offset:53680
	ds_write_b16_d16_hi v162, v41 offset:62896
	ds_write_b16 v161, v38 offset:53824
	ds_write_b16 v162, v42 offset:63040
	ds_write_b16_d16_hi v161, v38 offset:53968
	ds_write_b16_d16_hi v162, v42 offset:63184
	ds_write_b16 v161, v39 offset:54112
	ds_write_b16 v162, v43 offset:63328
	ds_write_b16_d16_hi v161, v39 offset:54256
	ds_write_b16_d16_hi v162, v43 offset:63472
	ds_write_b16_d16_hi v161, v83 offset:34816
	v_mul_f32_e32 v83, v220, v72
	v_bfe_u32 v87, v83, 16, 1
	v_add3_u32 v83, v83, v87, s31
	ds_write_b16_d16_hi v162, v83 offset:44032
	v_mul_f32_e32 v83, v220, v79
	v_bfe_u32 v87, v83, 16, 1
	v_add3_u32 v83, v83, v87, s31
	ds_write_b16_d16_hi v161, v83 offset:34960
	v_mul_f32_e32 v83, v220, v73
	v_bfe_u32 v87, v83, 16, 1
	v_add3_u32 v83, v83, v87, s31
	ds_write_b16_d16_hi v162, v83 offset:44176
	v_mul_f32_e32 v83, v220, v84
	v_bfe_u32 v87, v83, 16, 1
	v_add3_u32 v83, v83, v87, s31
	ds_write_b16_d16_hi v161, v83 offset:35104
	v_mul_f32_e32 v83, v220, v76
	v_bfe_u32 v87, v83, 16, 1
	v_add3_u32 v83, v83, v87, s31
	ds_write_b16_d16_hi v162, v83 offset:44320
	v_mul_f32_e32 v83, v220, v85
	v_bfe_u32 v87, v83, 16, 1
	v_add3_u32 v83, v83, v87, s31
	ds_write_b16_d16_hi v161, v83 offset:35248
	v_mul_f32_e32 v83, v220, v77
	v_bfe_u32 v87, v83, 16, 1
	v_add3_u32 v83, v83, v87, s31
	ds_write_b16_d16_hi v162, v83 offset:44464
	v_mul_f32_e32 v83, v220, v80
	v_bfe_u32 v87, v83, 16, 1
	v_add3_u32 v83, v83, v87, s31
	ds_write_b16_d16_hi v161, v83 offset:35392
	v_mul_f32_e32 v83, v220, v74
	v_bfe_u32 v87, v83, 16, 1
	v_add3_u32 v83, v83, v87, s31
	ds_write_b16_d16_hi v162, v83 offset:44608
	v_mul_f32_e32 v83, v220, v81
	v_bfe_u32 v87, v83, 16, 1
	v_add3_u32 v83, v83, v87, s31
	ds_write_b16_d16_hi v161, v83 offset:35536
	v_mul_f32_e32 v83, v220, v75
	v_bfe_u32 v87, v83, 16, 1
	v_add3_u32 v83, v83, v87, s31
	ds_write_b16_d16_hi v162, v83 offset:44752
	v_mul_f32_e32 v83, v220, v82
	v_bfe_u32 v87, v83, 16, 1
	v_add3_u32 v83, v83, v87, s31
	ds_write_b16_d16_hi v161, v83 offset:35680
	v_mul_f32_e32 v83, v220, v86
	v_bfe_u32 v87, v83, 16, 1
	v_add3_u32 v83, v83, v87, s31
	ds_write_b16_d16_hi v162, v83 offset:44896
	v_mul_f32_e32 v83, v220, v121
	v_bfe_u32 v87, v83, 16, 1
	v_add3_u32 v83, v83, v87, s31
	v_mov_b32_e32 v126, v141
	ds_write_b16_d16_hi v161, v83 offset:35824
	v_mul_f32_e32 v83, v220, v120
	v_pk_mul_f32 v[126:127], v[126:127], s[26:27] op_sel_hi:[1,0]
	v_bfe_u32 v87, v83, 16, 1
	v_pk_mul_f32 v[136:137], v[148:149], s[26:27] op_sel_hi:[1,0]
	v_add3_u32 v83, v83, v87, s31
	v_and_b32_sdwa v122, v127, v207 dst_sel:DWORD dst_unused:UNUSED_PAD src0_sel:WORD_1 src1_sel:DWORD
	ds_write_b16_d16_hi v162, v83 offset:45040
	v_and_b32_sdwa v83, v137, v207 dst_sel:DWORD dst_unused:UNUSED_PAD src0_sel:WORD_1 src1_sel:DWORD
	v_add3_u32 v122, v127, v122, s31
	v_add3_u32 v83, v137, v83, s31
	v_and_b32_e32 v122, 0xffff0000, v122
	v_cvt_pk_bf16_f32 v140, v136, v126
	v_pk_mul_f32 v[126:127], v[130:131], s[26:27] op_sel_hi:[1,0]
	v_or_b32_sdwa v141, v122, v83 dst_sel:DWORD dst_unused:UNUSED_PAD src0_sel:DWORD src1_sel:WORD_1
	v_pk_mul_f32 v[130:131], v[142:143], s[26:27] op_sel_hi:[1,0]
	v_and_b32_sdwa v87, v127, v207 dst_sel:DWORD dst_unused:UNUSED_PAD src0_sel:WORD_1 src1_sel:DWORD
	v_and_b32_sdwa v122, v126, v207 dst_sel:DWORD dst_unused:UNUSED_PAD src0_sel:WORD_1 src1_sel:DWORD
	v_add3_u32 v122, v126, v122, s31
	v_add3_u32 v87, v127, v87, s31
	v_and_b32_sdwa v126, v131, v207 dst_sel:DWORD dst_unused:UNUSED_PAD src0_sel:WORD_1 src1_sel:DWORD
	v_and_b32_sdwa v127, v130, v207 dst_sel:DWORD dst_unused:UNUSED_PAD src0_sel:WORD_1 src1_sel:DWORD
	v_add3_u32 v126, v131, v126, s31
	v_add3_u32 v127, v130, v127, s31
	v_and_b32_e32 v126, 0xffff0000, v126
	v_and_b32_e32 v127, 0xffff0000, v127
	v_or_b32_sdwa v143, v126, v87 dst_sel:DWORD dst_unused:UNUSED_PAD src0_sel:DWORD src1_sel:WORD_1
	v_or_b32_sdwa v142, v127, v122 dst_sel:DWORD dst_unused:UNUSED_PAD src0_sel:DWORD src1_sel:WORD_1
	v_pk_mul_f32 v[126:127], v[144:145], s[26:27] op_sel_hi:[1,0]
	v_mov_b32_e32 v122, v129
	v_pk_mul_f32 v[122:123], v[122:123], s[26:27] op_sel_hi:[1,0]
	v_pk_mul_f32 v[124:125], v[124:125], s[26:27] op_sel_hi:[1,0]
	v_cvt_pk_bf16_f32 v123, v127, v123
	v_cvt_pk_bf16_f32 v122, v126, v122
	v_pk_mul_f32 v[126:127], v[146:147], s[26:27] op_sel_hi:[1,0]
	v_add_u32_e32 v83, v163, v160
	v_cvt_pk_bf16_f32 v125, v125, v127
	v_cvt_pk_bf16_f32 v124, v124, v126
	ds_write_b128 v83, v[122:125] offset:128
	v_and_b32_sdwa v122, v78, v207 dst_sel:DWORD dst_unused:UNUSED_PAD src0_sel:WORD_1 src1_sel:DWORD
	v_add3_u32 v78, v78, v122, s31
	v_and_b32_sdwa v122, v79, v207 dst_sel:DWORD dst_unused:UNUSED_PAD src0_sel:WORD_1 src1_sel:DWORD
	v_add3_u32 v79, v79, v122, s31
	v_and_b32_e32 v87, 0xffff0000, v79
	v_cvt_pk_bf16_f32 v79, v84, v85
	v_and_b32_sdwa v85, v80, v207 dst_sel:DWORD dst_unused:UNUSED_PAD src0_sel:WORD_1 src1_sel:DWORD
	v_add3_u32 v80, v80, v85, s31
	v_and_b32_sdwa v85, v81, v207 dst_sel:DWORD dst_unused:UNUSED_PAD src0_sel:WORD_1 src1_sel:DWORD
	v_add3_u32 v81, v81, v85, s31
	v_and_b32_e32 v85, 0xffff0000, v81
	v_or_b32_sdwa v78, v87, v78 dst_sel:DWORD dst_unused:UNUSED_PAD src0_sel:DWORD src1_sel:WORD_1
	v_cvt_pk_bf16_f32 v81, v82, v121
	v_or_b32_sdwa v80, v85, v80 dst_sel:DWORD dst_unused:UNUSED_PAD src0_sel:DWORD src1_sel:WORD_1
	ds_write_b128 v83, v[78:81] offset:17408
	v_and_b32_sdwa v79, v72, v207 dst_sel:DWORD dst_unused:UNUSED_PAD src0_sel:WORD_1 src1_sel:DWORD
	v_add3_u32 v72, v72, v79, s31
	v_and_b32_sdwa v79, v73, v207 dst_sel:DWORD dst_unused:UNUSED_PAD src0_sel:WORD_1 src1_sel:DWORD
	v_add3_u32 v73, v73, v79, s31
	v_and_b32_e32 v78, 0xffff0000, v73
	v_cvt_pk_bf16_f32 v73, v76, v77
	v_and_b32_sdwa v77, v74, v207 dst_sel:DWORD dst_unused:UNUSED_PAD src0_sel:WORD_1 src1_sel:DWORD
	v_or_b32_sdwa v72, v78, v72 dst_sel:DWORD dst_unused:UNUSED_PAD src0_sel:DWORD src1_sel:WORD_1
	v_add3_u32 v74, v74, v77, s31
	v_and_b32_sdwa v78, v75, v207 dst_sel:DWORD dst_unused:UNUSED_PAD src0_sel:WORD_1 src1_sel:DWORD
	v_add3_u32 v75, v75, v78, s31
	v_and_b32_e32 v78, 0xffff0000, v75
	s_add_i32 s82, s82, 1
	v_cvt_pk_bf16_f32 v75, v86, v120
	v_or_b32_sdwa v74, v78, v74 dst_sel:DWORD dst_unused:UNUSED_PAD src0_sel:DWORD src1_sel:WORD_1
	s_cmp_ge_i32 s82, s15
	ds_write_b128 v83, v[140:143]
	ds_write_b128 v83, v[72:75] offset:17536
	s_cbranch_scc1 .LBB0_410
; __device__ __forceinline__ void ret_issue(KP p, RetRaw& R, int tid_, int mode, int base, int rev, int h, int rope, int t0) {
;   const u16* zcr = (const u16*)(p->ws + OFF_ZCR);
;   const float* rc = (const float*)(p->ws + OFF_ROPE);
;   const float* rs = rc + TL * 64;
;   const int i = tid_ >> 3, g = tid_ & 7;
;   const int nr = rev ? (base + 63 - i) : (base + i);
;   const u16* zr = zcr + (size_t)nr * CRC + 1536 + h * 128;
;   R.k1 = *(const uint4*)(zr + 768 + g * 8); R.k2 = *(const uint4*)(zr + 768 + 64 + g * 8);
;   R.v1 = *(const uint4*)(zr + 1536 + g * 8); R.v2 = *(const uint4*)(zr + 1536 + 64 + g * 8);
;   if (mode == 0) { R.q1 = *(const uint4*)(zr + g * 8); R.q2 = *(const uint4*)(zr + 64 + g * 8); }
;   if (rope) {
;     const int t = t0 + (rev ? (63 - i) : i);
;     const float* cp = rc + (size_t)t * 64 + g * 8; const float* sp = rs + (size_t)t * 64 + g * 8;
;     R.c0 = *(const float4*)cp; R.c1 = *(const float4*)(cp + 4); R.s0 = *(const float4*)sp; R.s1 = *(const float4*)(sp + 4);
;   }
; }
	v_mov_b64_e32 v[32:33], s[84:85]
	v_mad_i64_i32 v[32:33], s[76:77], v219, s37, v[32:33]
	v_lshl_add_u64 v[32:33], s[38:39], 1, v[32:33]
	v_lshl_add_u64 v[40:41], v[32:33], 0, v[132:133]
	s_mov_b64 s[76:77], 0x1d000c00
	v_add_co_u32_e32 v44, vcc, 0x1d000000, v40
	v_lshl_add_u64 v[52:53], v[40:41], 0, s[76:77]
	s_nop 0
	v_addc_co_u32_e32 v45, vcc, 0, v41, vcc
	global_load_dwordx4 v[32:35], v[52:53], off offset:1664
	global_load_dwordx4 v[36:39], v[52:53], off offset:3072
	global_load_dwordx4 v[40:43], v[52:53], off offset:3200
	s_nop 0
	global_load_dwordx4 v[44:47], v[44:45], off offset:3072
	s_nop 0
	global_load_dwordx4 v[48:51], v[52:53], off offset:1536
	s_nop 0
	global_load_dwordx4 v[52:55], v[52:53], off offset:128
	s_and_b64 vcc, exec, s[74:75]
	s_cbranch_vccnz .LBB0_410
	v_lshl_add_u64 v[56:57], s[84:85], 0, v[116:117]
	v_add_co_u32_e32 v58, vcc, 0x100000, v56
	s_mov_b64 s[76:77], 0x100000
	s_nop 0
	v_addc_co_u32_e32 v59, vcc, 0, v57, vcc
	v_lshl_add_u64 v[60:61], v[56:57], 0, s[76:77]
	s_mov_b64 s[76:77], 0x500000
	v_add_co_u32_e32 v62, vcc, 0x500000, v56
	v_lshl_add_u64 v[64:65], v[56:57], 0, s[76:77]
	s_nop 0
	v_addc_co_u32_e32 v63, vcc, 0, v57, vcc
	global_load_dwordx4 v[56:59], v[58:59], off
	s_nop 0
	global_load_dwordx4 v[68:71], v[62:63], off
	s_nop 0
	global_load_dwordx4 v[60:63], v[60:61], off offset:16
	s_nop 0
	global_load_dwordx4 v[64:67], v[64:65], off offset:16

; #define UFOR(v, n) _Pragma("unroll") for (int v = 0; v < (n); ++v)
; __device__ __forceinline__ unsigned pk2(float a, float b) { return (unsigned)f2bf(a) | ((unsigned)f2bf(b) << 16); }
; __device__ __forceinline__ void ret_stage(const RetRaw& R, int tid_, int mode, int rope, float zf, float zb) {
;     ...
;   unpack8(R.k1, k1); unpack8(R.k2, k2); unpack8(R.v1, v1); unpack8(R.v2, v2);
;   if (mode == 0) { unpack8(R.q1, q1); unpack8(R.q2, q2); }
;   if (rope) {
;     const float cc[8] = {R.c0.x, R.c0.y, R.c0.z, R.c0.w, R.c1.x, R.c1.y, R.c1.z, R.c1.w};
;     const float ss[8] = {R.s0.x, R.s0.y, R.s0.z, R.s0.w, R.s1.x, R.s1.y, R.s1.z, R.s1.w};
;     UFOR(x, 8) {
;       const float c = cc[x], s = ss[x];
;       const float a = k1[x], b = k2[x]; k1[x] = a * c - b * s; k2[x] = a * s + b * c;
;       if (mode == 0) { const float a2 = q1[x], b2 = q2[x]; q1[x] = a2 * c - b2 * s; q2[x] = a2 * s + b2 * c; }
;     }
;   }
; __device__ __forceinline__ void ret_pass(KP p, int tid_, int dir, int n0, int nch, int h, int rope, int tseg0, f32x4* RT, float* scr) {
;     ...
;     UFOR(n, 8) {
;       uint2 pk; pk.x = pk2(RT[n][0], RT[n][1]); pk.y = pk2(RT[n][2], RT[n][3]);
;       *(uint2*)(smem + R_RT + (w * 16 + fr) * 272 + (n * 16 + fq * 4) * 2) = pk;
;     }
;     ret_stage(R, tid_, 0, rope, pw[63 - (tid_ >> 3)], 0.f);
.LBB0_439:
	v_cvt_pk_bf16_f32 v73, v6, v7
	v_cvt_pk_bf16_f32 v72, v4, v5
	v_add_u32_e32 v76, v157, v158
	v_cvt_pk_bf16_f32 v75, v2, v3
	v_cvt_pk_bf16_f32 v74, v0, v1
	s_waitcnt lgkmcnt(0)
	s_barrier
	ds_write2_b64 v76, v[72:73], v[74:75] offset1:4
	v_cvt_pk_bf16_f32 v73, v10, v11
	v_cvt_pk_bf16_f32 v72, v8, v9
	v_cvt_pk_bf16_f32 v75, v14, v15
	v_cvt_pk_bf16_f32 v74, v12, v13
	ds_write2_b64 v76, v[72:73], v[74:75] offset0:8 offset1:12
	v_cvt_pk_bf16_f32 v73, v18, v19
	v_cvt_pk_bf16_f32 v72, v16, v17
	v_cvt_pk_bf16_f32 v75, v22, v23
	v_cvt_pk_bf16_f32 v74, v20, v21
	ds_write2_b64 v76, v[72:73], v[74:75] offset0:16 offset1:20
	v_cvt_pk_bf16_f32 v73, v26, v27
	v_cvt_pk_bf16_f32 v72, v24, v25
	v_cvt_pk_bf16_f32 v75, v30, v31
	v_cvt_pk_bf16_f32 v74, v28, v29
	ds_write2_b64 v76, v[72:73], v[74:75] offset0:24 offset1:28
	ds_read_b32 v219, v193
	s_waitcnt vmcnt(1)
	v_lshlrev_b32_e32 v82, 16, v51
	v_lshlrev_b32_e32 v78, 16, v48
	v_and_b32_e32 v79, 0xffff0000, v48
	v_lshlrev_b32_e32 v72, 16, v32
	v_and_b32_e32 v73, 0xffff0000, v32
	v_lshlrev_b32_e32 v84, 16, v49
	v_and_b32_e32 v85, 0xffff0000, v49
	v_lshlrev_b32_e32 v76, 16, v33
	v_and_b32_e32 v77, 0xffff0000, v33
	v_lshlrev_b32_e32 v80, 16, v50
	v_and_b32_e32 v81, 0xffff0000, v50
	v_lshlrev_b32_e32 v74, 16, v34
	v_and_b32_e32 v75, 0xffff0000, v34
	v_lshlrev_b32_e32 v86, 16, v35
	v_and_b32_e32 v121, 0xffff0000, v51
	v_and_b32_e32 v120, 0xffff0000, v35
	v_lshlrev_b32_e32 v131, 16, v47
	v_lshlrev_b32_e32 v140, 16, v44
	v_and_b32_e32 v141, 0xffff0000, v44
	s_waitcnt vmcnt(0)
	v_lshlrev_b32_e32 v128, 16, v52
	v_and_b32_e32 v129, 0xffff0000, v52
	v_lshlrev_b32_e32 v126, 16, v45
	v_and_b32_e32 v127, 0xffff0000, v45
	v_lshlrev_b32_e32 v122, 16, v53
	v_and_b32_e32 v123, 0xffff0000, v53
	v_lshlrev_b32_e32 v130, 16, v46
	v_and_b32_e32 v151, 0xffff0000, v46
	v_lshlrev_b32_e32 v124, 16, v54
	v_and_b32_e32 v147, 0xffff0000, v54
	v_lshlrev_b32_e32 v125, 16, v55
	v_and_b32_e32 v143, 0xffff0000, v47
	s_and_b64 vcc, exec, s[74:75]
	v_and_b32_e32 v142, 0xffff0000, v55
	s_cbranch_vccnz .LBB0_441
	v_mov_b32_e32 v238, v67
	v_mov_b32_e32 v239, v63
	v_mov_b32_e32 v146, v124
	v_mul_f32_e32 v124, v62, v82
	v_mul_f32_e32 v228, v66, v82
	v_pk_mul_f32 v[82:83], v[238:239], v[120:121]
	v_mov_b32_e32 v150, v130
	v_mul_f32_e32 v130, v66, v86
	v_mul_f32_e32 v230, v62, v131
	v_mul_f32_e32 v232, v66, v125
	v_mul_f32_e32 v234, v66, v131
	v_mul_f32_e32 v236, v62, v125
	v_mov_b32_e32 v125, v83
	v_mov_b32_e32 v131, v82
	v_pk_add_f32 v[82:83], v[124:125], v[130:131] neg_lo:[0,1] neg_hi:[0,1]
	v_mov_b32_e32 v124, v63
	v_mov_b32_e32 v125, v67
	v_pk_mul_f32 v[120:121], v[124:125], v[120:121]
	v_pk_mul_f32 v[136:137], v[68:69], v[72:73]
	v_mov_b32_e32 v87, v120
	v_mov_b32_e32 v229, v121
	v_pk_mul_f32 v[120:121], v[238:239], v[142:143]
	v_pk_mul_f32 v[138:139], v[68:69], v[78:79]
	v_mov_b32_e32 v231, v121
	v_mov_b32_e32 v233, v120
	v_pk_mul_f32 v[120:121], v[124:125], v[142:143]
	v_pk_mul_f32 v[144:145], v[68:69], v[128:129]
	v_pk_mul_f32 v[208:209], v[68:69], v[140:141]
	v_pk_mul_f32 v[148:149], v[70:71], v[76:77]
	v_pk_mul_f32 v[214:215], v[70:71], v[122:123]
	v_pk_mul_f32 v[216:217], v[70:71], v[126:127]
	v_pk_mul_f32 v[224:225], v[64:65], v[146:147]
	v_pk_mul_f32 v[226:227], v[64:65], v[150:151]
	v_mul_f32_e32 v86, v62, v86
	v_mov_b32_e32 v237, v120
	v_mov_b32_e32 v235, v121
	v_pk_mul_f32 v[210:211], v[70:71], v[84:85]
	v_pk_mul_f32 v[220:221], v[64:65], v[74:75]
	v_pk_mul_f32 v[222:223], v[64:65], v[80:81]
	v_pk_fma_f32 v[78:79], v[56:57], v[78:79], v[136:137] neg_lo:[0,0,1] neg_hi:[0,0,1]
	v_pk_fma_f32 v[84:85], v[58:59], v[84:85], v[148:149] neg_lo:[0,0,1] neg_hi:[0,0,1]
	v_pk_fma_f32 v[72:73], v[56:57], v[72:73], v[138:139]
	v_pk_add_f32 v[86:87], v[86:87], v[228:229]
	v_pk_fma_f32 v[148:149], v[56:57], v[140:141], v[144:145] neg_lo:[0,0,1] neg_hi:[0,0,1]
	v_pk_fma_f32 v[126:127], v[58:59], v[126:127], v[214:215] neg_lo:[0,0,1] neg_hi:[0,0,1]
	v_pk_fma_f32 v[130:131], v[60:61], v[150:151], v[224:225] neg_lo:[0,0,1] neg_hi:[0,0,1]
	v_pk_add_f32 v[136:137], v[230:231], v[232:233] neg_lo:[0,1] neg_hi:[0,1]
	v_pk_fma_f32 v[144:145], v[56:57], v[128:129], v[208:209]
	v_pk_fma_f32 v[122:123], v[58:59], v[122:123], v[216:217]
	v_pk_fma_f32 v[124:125], v[60:61], v[146:147], v[226:227]
	v_pk_add_f32 v[138:139], v[236:237], v[234:235]
	v_pk_fma_f32 v[80:81], v[60:61], v[80:81], v[220:221] neg_lo:[0,0,1] neg_hi:[0,0,1]
	v_pk_fma_f32 v[76:77], v[58:59], v[76:77], v[210:211]
	v_pk_fma_f32 v[74:75], v[60:61], v[74:75], v[222:223]
	v_mov_b32_e32 v120, v87
	v_mov_b32_e32 v121, v83
	v_mov_b32_e32 v129, v145
	v_mov_b32_e32 v145, v122
	v_mov_b32_e32 v146, v125
	v_mov_b32_e32 v125, v138
	v_mov_b32_e32 v147, v139
	v_mov_b32_e32 v141, v149
	v_mov_b32_e32 v149, v126
	v_mov_b32_e32 v142, v131
	v_mov_b32_e32 v131, v136
	v_mov_b32_e32 v143, v137
	s_branch .LBB0_442

; #define UFOR(v, n) _Pragma("unroll") for (int v = 0; v < (n); ++v)
; __device__ __forceinline__ void ret_stage(const RetRaw& R, int tid_, int mode, int rope, float zf, float zb) {
;     ...
;   u16* VT = (u16*)(smem + R_VT);
;   const int isw = i ^ (g << 3);
;   UFOR(x, 8) { VT[(g * 8 + x) * 72 + isw] = f2bf(v1[x]); VT[(64 + g * 8 + x) * 72 + isw] = f2bf(v2[x]); }
;   u16* KT = (u16*)(smem + R_KT);
;   UFOR(x, 8) { KT[(g * 8 + x) * 72 + isw] = f2bf(k1[x] * zf); KT[(64 + g * 8 + x) * 72 + isw] = f2bf(k2[x] * zf); }
;   if (mode == 1) {
;     u16* KB = (u16*)(smem + R_KT2B);
;     UFOR(x, 8) { KB[(g * 8 + x) * 72 + isw] = f2bf(k1[x] * zb); KB[(64 + g * 8 + x) * 72 + isw] = f2bf(k2[x] * zb); }
;   } else {
;     const float sc = 0.08838834764831845f;
;     UFOR(x, 8) { q1[x] *= sc; q2[x] *= sc; }
;     *(uint4*)(smem + R_QS + i * 272 + g * 16) = pack8(q1); *(uint4*)(smem + R_QS + i * 272 + 128 + g * 16) = pack8(q2);
;     *(uint4*)(smem + R_KS + i * 272 + g * 16) = pack8(k1); *(uint4*)(smem + R_KS + i * 272 + 128 + g * 16) = pack8(k2);
;   }
.LBB0_442:
	s_waitcnt lgkmcnt(0)
	v_mul_f32_e32 v83, v219, v78
	v_bfe_u32 v87, v83, 16, 1
	v_add3_u32 v83, v83, v87, s31
	ds_write_b16 v161, v36 offset:53248
	ds_write_b16 v162, v40 offset:62464
	ds_write_b16_d16_hi v161, v36 offset:53392
	ds_write_b16_d16_hi v162, v40 offset:62608
	ds_write_b16 v161, v37 offset:53536
	ds_write_b16 v162, v41 offset:62752
	ds_write_b16_d16_hi v161, v37 offset:53680
	ds_write_b16_d16_hi v162, v41 offset:62896
	ds_write_b16 v161, v38 offset:53824
	ds_write_b16 v162, v42 offset:63040
	ds_write_b16_d16_hi v161, v38 offset:53968
	ds_write_b16_d16_hi v162, v42 offset:63184
	ds_write_b16 v161, v39 offset:54112
	ds_write_b16 v162, v43 offset:63328
	ds_write_b16_d16_hi v161, v39 offset:54256
	ds_write_b16_d16_hi v162, v43 offset:63472
	ds_write_b16_d16_hi v161, v83 offset:34816
	v_mul_f32_e32 v83, v219, v72
	v_bfe_u32 v87, v83, 16, 1
	v_add3_u32 v83, v83, v87, s31
	ds_write_b16_d16_hi v162, v83 offset:44032
	v_mul_f32_e32 v83, v219, v79
	v_bfe_u32 v87, v83, 16, 1
	v_add3_u32 v83, v83, v87, s31
	ds_write_b16_d16_hi v161, v83 offset:34960
	v_mul_f32_e32 v83, v219, v73
	v_bfe_u32 v87, v83, 16, 1
	v_add3_u32 v83, v83, v87, s31
	ds_write_b16_d16_hi v162, v83 offset:44176
	v_mul_f32_e32 v83, v219, v84
	v_bfe_u32 v87, v83, 16, 1
	v_add3_u32 v83, v83, v87, s31
	ds_write_b16_d16_hi v161, v83 offset:35104
	v_mul_f32_e32 v83, v219, v76
	v_bfe_u32 v87, v83, 16, 1
	v_add3_u32 v83, v83, v87, s31
	ds_write_b16_d16_hi v162, v83 offset:44320
	v_mul_f32_e32 v83, v219, v85
	v_bfe_u32 v87, v83, 16, 1
	v_add3_u32 v83, v83, v87, s31
	ds_write_b16_d16_hi v161, v83 offset:35248
	v_mul_f32_e32 v83, v219, v77
	v_bfe_u32 v87, v83, 16, 1
	v_add3_u32 v83, v83, v87, s31
	ds_write_b16_d16_hi v162, v83 offset:44464
	v_mul_f32_e32 v83, v219, v80
	v_bfe_u32 v87, v83, 16, 1
	v_add3_u32 v83, v83, v87, s31
	ds_write_b16_d16_hi v161, v83 offset:35392
	v_mul_f32_e32 v83, v219, v74
	v_bfe_u32 v87, v83, 16, 1
	v_add3_u32 v83, v83, v87, s31
	ds_write_b16_d16_hi v162, v83 offset:44608
	v_mul_f32_e32 v83, v219, v81
	v_bfe_u32 v87, v83, 16, 1
	v_add3_u32 v83, v83, v87, s31
	ds_write_b16_d16_hi v161, v83 offset:35536
	v_mul_f32_e32 v83, v219, v75
	v_bfe_u32 v87, v83, 16, 1
	v_add3_u32 v83, v83, v87, s31
	ds_write_b16_d16_hi v162, v83 offset:44752
	v_mul_f32_e32 v83, v219, v82
	v_bfe_u32 v87, v83, 16, 1
	v_add3_u32 v83, v83, v87, s31
	ds_write_b16_d16_hi v161, v83 offset:35680
	v_mul_f32_e32 v83, v219, v86
	v_bfe_u32 v87, v83, 16, 1
	v_add3_u32 v83, v83, v87, s31
	ds_write_b16_d16_hi v162, v83 offset:44896
	v_mul_f32_e32 v83, v219, v121
	v_bfe_u32 v87, v83, 16, 1
	v_add3_u32 v83, v83, v87, s31
	v_mov_b32_e32 v126, v141
	ds_write_b16_d16_hi v161, v83 offset:35824
	v_mul_f32_e32 v83, v219, v120
	v_pk_mul_f32 v[126:127], v[126:127], s[26:27] op_sel_hi:[1,0]
	v_bfe_u32 v87, v83, 16, 1
	v_pk_mul_f32 v[136:137], v[148:149], s[26:27] op_sel_hi:[1,0]
	v_add3_u32 v83, v83, v87, s31
	v_and_b32_sdwa v122, v127, v207 dst_sel:DWORD dst_unused:UNUSED_PAD src0_sel:WORD_1 src1_sel:DWORD
	ds_write_b16_d16_hi v162, v83 offset:45040
	v_and_b32_sdwa v83, v137, v207 dst_sel:DWORD dst_unused:UNUSED_PAD src0_sel:WORD_1 src1_sel:DWORD
	v_add3_u32 v122, v127, v122, s31
	v_add3_u32 v83, v137, v83, s31
	v_and_b32_e32 v122, 0xffff0000, v122
	v_cvt_pk_bf16_f32 v140, v136, v126
	v_pk_mul_f32 v[126:127], v[130:131], s[26:27] op_sel_hi:[1,0]
	v_or_b32_sdwa v141, v122, v83 dst_sel:DWORD dst_unused:UNUSED_PAD src0_sel:DWORD src1_sel:WORD_1
	v_pk_mul_f32 v[130:131], v[142:143], s[26:27] op_sel_hi:[1,0]
	v_and_b32_sdwa v87, v127, v207 dst_sel:DWORD dst_unused:UNUSED_PAD src0_sel:WORD_1 src1_sel:DWORD
	v_and_b32_sdwa v122, v126, v207 dst_sel:DWORD dst_unused:UNUSED_PAD src0_sel:WORD_1 src1_sel:DWORD
	v_add3_u32 v122, v126, v122, s31
	v_add3_u32 v87, v127, v87, s31
	v_and_b32_sdwa v126, v131, v207 dst_sel:DWORD dst_unused:UNUSED_PAD src0_sel:WORD_1 src1_sel:DWORD
	v_and_b32_sdwa v127, v130, v207 dst_sel:DWORD dst_unused:UNUSED_PAD src0_sel:WORD_1 src1_sel:DWORD
	v_add3_u32 v126, v131, v126, s31
	v_add3_u32 v127, v130, v127, s31
	v_and_b32_e32 v126, 0xffff0000, v126
	v_and_b32_e32 v127, 0xffff0000, v127
	v_or_b32_sdwa v143, v126, v87 dst_sel:DWORD dst_unused:UNUSED_PAD src0_sel:DWORD src1_sel:WORD_1
	v_or_b32_sdwa v142, v127, v122 dst_sel:DWORD dst_unused:UNUSED_PAD src0_sel:DWORD src1_sel:WORD_1
	v_pk_mul_f32 v[126:127], v[144:145], s[26:27] op_sel_hi:[1,0]
	v_mov_b32_e32 v122, v129
	v_pk_mul_f32 v[122:123], v[122:123], s[26:27] op_sel_hi:[1,0]
	v_pk_mul_f32 v[124:125], v[124:125], s[26:27] op_sel_hi:[1,0]
	v_cvt_pk_bf16_f32 v123, v127, v123
	v_cvt_pk_bf16_f32 v122, v126, v122
	v_pk_mul_f32 v[126:127], v[146:147], s[26:27] op_sel_hi:[1,0]
	v_add_u32_e32 v83, v163, v160
	v_cvt_pk_bf16_f32 v125, v125, v127
	v_cvt_pk_bf16_f32 v124, v124, v126
	ds_write_b128 v83, v[122:125] offset:128
	v_and_b32_sdwa v122, v78, v207 dst_sel:DWORD dst_unused:UNUSED_PAD src0_sel:WORD_1 src1_sel:DWORD
	v_add3_u32 v78, v78, v122, s31
	v_and_b32_sdwa v122, v79, v207 dst_sel:DWORD dst_unused:UNUSED_PAD src0_sel:WORD_1 src1_sel:DWORD
	v_add3_u32 v79, v79, v122, s31
	v_and_b32_e32 v87, 0xffff0000, v79
	v_cvt_pk_bf16_f32 v79, v84, v85
	v_and_b32_sdwa v85, v80, v207 dst_sel:DWORD dst_unused:UNUSED_PAD src0_sel:WORD_1 src1_sel:DWORD
	v_add3_u32 v80, v80, v85, s31
	v_and_b32_sdwa v85, v81, v207 dst_sel:DWORD dst_unused:UNUSED_PAD src0_sel:WORD_1 src1_sel:DWORD
	v_add3_u32 v81, v81, v85, s31
	v_and_b32_e32 v85, 0xffff0000, v81
	v_or_b32_sdwa v78, v87, v78 dst_sel:DWORD dst_unused:UNUSED_PAD src0_sel:DWORD src1_sel:WORD_1
	v_cvt_pk_bf16_f32 v81, v82, v121
	v_or_b32_sdwa v80, v85, v80 dst_sel:DWORD dst_unused:UNUSED_PAD src0_sel:DWORD src1_sel:WORD_1
	ds_write_b128 v83, v[78:81] offset:17408
	v_and_b32_sdwa v79, v72, v207 dst_sel:DWORD dst_unused:UNUSED_PAD src0_sel:WORD_1 src1_sel:DWORD
	v_add3_u32 v72, v72, v79, s31
	v_and_b32_sdwa v79, v73, v207 dst_sel:DWORD dst_unused:UNUSED_PAD src0_sel:WORD_1 src1_sel:DWORD
	v_add3_u32 v73, v73, v79, s31
	v_and_b32_e32 v78, 0xffff0000, v73
	v_cvt_pk_bf16_f32 v73, v76, v77
	v_and_b32_sdwa v77, v74, v207 dst_sel:DWORD dst_unused:UNUSED_PAD src0_sel:WORD_1 src1_sel:DWORD
	v_or_b32_sdwa v72, v78, v72 dst_sel:DWORD dst_unused:UNUSED_PAD src0_sel:DWORD src1_sel:WORD_1
	v_add3_u32 v74, v74, v77, s31
	v_and_b32_sdwa v78, v75, v207 dst_sel:DWORD dst_unused:UNUSED_PAD src0_sel:WORD_1 src1_sel:DWORD
	v_add3_u32 v75, v75, v78, s31
	v_and_b32_e32 v78, 0xffff0000, v75
	s_add_i32 s6, s6, 1
	v_cvt_pk_bf16_f32 v75, v86, v120
	v_or_b32_sdwa v74, v78, v74 dst_sel:DWORD dst_unused:UNUSED_PAD src0_sel:DWORD src1_sel:WORD_1
	s_cmp_ge_i32 s6, s15
	ds_write_b128 v83, v[140:143]
	ds_write_b128 v83, v[72:75] offset:17536
	s_cbranch_scc1 .LBB0_445
; __device__ __forceinline__ void ret_issue(KP p, RetRaw& R, int tid_, int mode, int base, int rev, int h, int rope, int t0) {
;   const u16* zcr = (const u16*)(p->ws + OFF_ZCR);
;   const float* rc = (const float*)(p->ws + OFF_ROPE);
;   const float* rs = rc + TL * 64;
;   const int i = tid_ >> 3, g = tid_ & 7;
;   const int nr = rev ? (base + 63 - i) : (base + i);
;   const u16* zr = zcr + (size_t)nr * CRC + 1536 + h * 128;
;   R.k1 = *(const uint4*)(zr + 768 + g * 8); R.k2 = *(const uint4*)(zr + 768 + 64 + g * 8);
;   R.v1 = *(const uint4*)(zr + 1536 + g * 8); R.v2 = *(const uint4*)(zr + 1536 + 64 + g * 8);
;   if (mode == 0) { R.q1 = *(const uint4*)(zr + g * 8); R.q2 = *(const uint4*)(zr + 64 + g * 8); }
;   if (rope) {
;     const int t = t0 + (rev ? (63 - i) : i);
;     const float* cp = rc + (size_t)t * 64 + g * 8; const float* sp = rs + (size_t)t * 64 + g * 8;
;     R.c0 = *(const float4*)cp; R.c1 = *(const float4*)(cp + 4); R.s0 = *(const float4*)sp; R.s1 = *(const float4*)(sp + 4);
;   }
; }
	v_mov_b64_e32 v[32:33], s[84:85]
	v_mad_i64_i32 v[32:33], s[40:41], v218, s37, v[32:33]
	v_lshl_add_u64 v[32:33], s[38:39], 1, v[32:33]
	v_lshl_add_u64 v[40:41], v[32:33], 0, v[132:133]
	s_mov_b64 s[0:1], 0x1d000c00
	v_add_co_u32_e32 v44, vcc, 0x1d000000, v40
	v_lshl_add_u64 v[52:53], v[40:41], 0, s[0:1]
	s_nop 0
	v_addc_co_u32_e32 v45, vcc, 0, v41, vcc
	global_load_dwordx4 v[32:35], v[52:53], off offset:1664
	global_load_dwordx4 v[36:39], v[52:53], off offset:3072
	global_load_dwordx4 v[40:43], v[52:53], off offset:3200
	s_nop 0
	global_load_dwordx4 v[44:47], v[44:45], off offset:3072
	s_nop 0
	global_load_dwordx4 v[48:51], v[52:53], off offset:1536
	s_nop 0
	global_load_dwordx4 v[52:55], v[52:53], off offset:128
	s_and_b64 vcc, exec, s[74:75]
	s_cbranch_vccnz .LBB0_445
	v_lshl_add_u64 v[56:57], s[84:85], 0, v[116:117]
	v_add_co_u32_e32 v58, vcc, 0x104000, v56
	s_mov_b64 s[40:41], 0x104000
	s_nop 0
	v_addc_co_u32_e32 v59, vcc, 0, v57, vcc
	v_lshl_add_u64 v[60:61], v[56:57], 0, s[40:41]
	s_mov_b64 s[40:41], 0x504000
	v_add_co_u32_e32 v62, vcc, 0x504000, v56
	v_lshl_add_u64 v[64:65], v[56:57], 0, s[40:41]
	s_nop 0
	v_addc_co_u32_e32 v63, vcc, 0, v57, vcc
	global_load_dwordx4 v[56:59], v[58:59], off
	s_nop 0
	global_load_dwordx4 v[68:71], v[62:63], off
	s_nop 0
	global_load_dwordx4 v[60:63], v[60:61], off offset:16
	s_nop 0
	global_load_dwordx4 v[64:67], v[64:65], off offset:16
